# baseline (speedup 1.0000x reference)
; __device__ __forceinline__ WTile wtile(KParams p, int t, int tid) {
;     ...
;   w.src += (size_t)(kt * 128 + (tid >> 5)) * w.N + nt * 128 + (tid & 31) * 4;
;   w.dst += pk_off(nt * 128 + (tid >> 4), kt * 128 + (tid & 15) * 8);
;   return w;
; }
; __device__ __forceinline__ F8 wload(const WTile& w) {
;   F8 v; const size_t st = (size_t)16 * w.N;
;   v.a = *(const float4*)(w.src);          v.b = *(const float4*)(w.src + st);     v.c = *(const float4*)(w.src + 2 * st); v.d = *(const float4*)(w.src + 3 * st);
;   v.e = *(const float4*)(w.src + 4 * st); v.f = *(const float4*)(w.src + 5 * st); v.g = *(const float4*)(w.src + 6 * st); v.h = *(const float4*)(w.src + 7 * st);
;   if (w.gain) {
;     ...
;     WSC(v.a, 0) WSC(v.b, 1) WSC(v.c, 2) WSC(v.d, 3) WSC(v.e, 4) WSC(v.f, 5) WSC(v.g, 6) WSC(v.h, 7)
;     ...
;   }
.LBB0_44:
	v_add_u32_e32 v1, s14, v1
	v_mad_i64_i32 v[2:3], s[10:11], s6, v1, 0
	s_lshl_b32 s10, s15, 7
	v_lshlrev_b32_e32 v1, 2, v36
	s_ashr_i32 s11, s10, 31
	v_and_b32_e32 v37, 0x7c, v1
	v_lshl_add_u64 v[2:3], v[2:3], 2, s[12:13]
	v_mov_b32_e32 v69, 0
	v_lshl_add_u64 v[2:3], s[10:11], 2, v[2:3]
	v_lshlrev_b32_e32 v68, 2, v37
	s_mov_b32 s7, 0
	v_lshl_add_u64 v[10:11], v[2:3], 0, v[68:69]
	s_lshl_b32 s6, s6, 6
	v_lshl_add_u64 v[12:13], v[10:11], 0, s[6:7]
	v_lshl_add_u64 v[18:19], v[12:13], 0, s[6:7]
	v_lshl_add_u64 v[20:21], v[18:19], 0, s[6:7]
	v_lshl_add_u64 v[26:27], v[20:21], 0, s[6:7]
	v_lshl_add_u64 v[28:29], v[26:27], 0, s[6:7]
	v_lshl_add_u64 v[38:39], v[28:29], 0, s[6:7]
	global_load_dwordx4 v[6:9], v[10:11], off nt
	global_load_dwordx4 v[2:5], v[12:13], off nt
	global_load_dwordx4 v[14:17], v[18:19], off nt
	s_nop 0
	global_load_dwordx4 v[10:13], v[20:21], off nt
	s_nop 0
	global_load_dwordx4 v[18:21], v[26:27], off nt
	global_load_dwordx4 v[22:25], v[28:29], off nt
	v_lshl_add_u64 v[40:41], v[38:39], 0, s[6:7]
	global_load_dwordx4 v[26:29], v[38:39], off nt
	global_load_dwordx4 v[30:33], v[40:41], off nt
	v_cmp_ne_u64_e32 vcc, 0, v[34:35]
	s_and_saveexec_b64 s[12:13], vcc
	s_cbranch_execz .LBB0_46
	global_load_dword v38, v[34:35], off
	global_load_dword v40, v[34:35], off offset:64
	global_load_dword v42, v[34:35], off offset:128
	global_load_dword v44, v[34:35], off offset:192
	global_load_dword v46, v[34:35], off offset:256
	global_load_dword v48, v[34:35], off offset:320
	global_load_dword v50, v[34:35], off offset:384
	global_load_dword v52, v[34:35], off offset:448
	s_waitcnt vmcnt(7)
	v_pk_mul_f32 v[6:7], v[6:7], v[38:39] op_sel_hi:[1,0]
	v_pk_mul_f32 v[8:9], v[8:9], v[38:39] op_sel_hi:[1,0]
	s_waitcnt vmcnt(6)
	v_pk_mul_f32 v[2:3], v[2:3], v[40:41] op_sel_hi:[1,0]
	v_pk_mul_f32 v[4:5], v[4:5], v[40:41] op_sel_hi:[1,0]
	s_waitcnt vmcnt(5)
	v_pk_mul_f32 v[14:15], v[14:15], v[42:43] op_sel_hi:[1,0]
	v_pk_mul_f32 v[16:17], v[16:17], v[42:43] op_sel_hi:[1,0]
	s_waitcnt vmcnt(4)
	v_pk_mul_f32 v[10:11], v[10:11], v[44:45] op_sel_hi:[1,0]
	v_pk_mul_f32 v[12:13], v[12:13], v[44:45] op_sel_hi:[1,0]
	s_waitcnt vmcnt(3)
	v_pk_mul_f32 v[18:19], v[18:19], v[46:47] op_sel_hi:[1,0]
	v_pk_mul_f32 v[20:21], v[20:21], v[46:47] op_sel_hi:[1,0]
	s_waitcnt vmcnt(2)
	v_pk_mul_f32 v[22:23], v[22:23], v[48:49] op_sel_hi:[1,0]
	v_pk_mul_f32 v[24:25], v[24:25], v[48:49] op_sel_hi:[1,0]
	s_waitcnt vmcnt(1)
	v_pk_mul_f32 v[26:27], v[26:27], v[50:51] op_sel_hi:[1,0]
	v_pk_mul_f32 v[28:29], v[28:29], v[50:51] op_sel_hi:[1,0]
	s_waitcnt vmcnt(0)
	v_pk_mul_f32 v[30:31], v[30:31], v[52:53] op_sel_hi:[1,0]
	v_pk_mul_f32 v[32:33], v[32:33], v[52:53] op_sel_hi:[1,0]

; __device__ __forceinline__ F8 wload(const WTile& w) {
;   F8 v; const size_t st = (size_t)16 * w.N;
;   v.a = *(const float4*)(w.src);          v.b = *(const float4*)(w.src + st);     v.c = *(const float4*)(w.src + 2 * st); v.d = *(const float4*)(w.src + 3 * st);
;   v.e = *(const float4*)(w.src + 4 * st); v.f = *(const float4*)(w.src + 5 * st); v.g = *(const float4*)(w.src + 6 * st); v.h = *(const float4*)(w.src + 7 * st);
;   if (w.gain) {
;     ...
;     WSC(v.a, 0) WSC(v.b, 1) WSC(v.c, 2) WSC(v.d, 3) WSC(v.e, 4) WSC(v.f, 5) WSC(v.g, 6) WSC(v.h, 7)
;     ...
;   }
.LBB0_53:
	v_add_u32_e32 v34, s22, v66
	v_mad_i64_i32 v[34:35], s[12:13], s16, v34, 0
	s_lshl_b32 s12, s6, 7
	s_ashr_i32 s13, s12, 31
	v_lshl_add_u64 v[34:35], v[34:35], 2, s[14:15]
	v_lshl_add_u64 v[34:35], s[12:13], 2, v[34:35]
	v_lshl_add_u64 v[42:43], v[34:35], 0, v[68:69]
	s_lshl_b32 s6, s16, 6
	v_lshl_add_u64 v[44:45], v[42:43], 0, s[6:7]
	v_lshl_add_u64 v[50:51], v[44:45], 0, s[6:7]
	v_lshl_add_u64 v[52:53], v[50:51], 0, s[6:7]
	v_lshl_add_u64 v[58:59], v[52:53], 0, s[6:7]
	v_lshl_add_u64 v[60:61], v[58:59], 0, s[6:7]
	v_lshl_add_u64 v[80:81], v[60:61], 0, s[6:7]
	global_load_dwordx4 v[34:37], v[42:43], off nt
	global_load_dwordx4 v[38:41], v[44:45], off nt
	s_nop 0
	global_load_dwordx4 v[42:45], v[50:51], off nt
	global_load_dwordx4 v[46:49], v[52:53], off nt
	global_load_dwordx4 v[54:57], v[58:59], off nt
	s_nop 0
	global_load_dwordx4 v[50:53], v[60:61], off nt
	v_lshl_add_u64 v[82:83], v[80:81], 0, s[6:7]
	global_load_dwordx4 v[62:65], v[80:81], off nt
	global_load_dwordx4 v[58:61], v[82:83], off nt
	v_cmp_ne_u64_e32 vcc, 0, v[72:73]
	s_and_saveexec_b64 s[14:15], vcc
	s_cbranch_execz .LBB0_47
	global_load_dword v80, v[72:73], off
	global_load_dword v82, v[72:73], off offset:64
	global_load_dword v84, v[72:73], off offset:128
	global_load_dword v86, v[72:73], off offset:192
	global_load_dword v88, v[72:73], off offset:256
	global_load_dword v90, v[72:73], off offset:320
	global_load_dword v92, v[72:73], off offset:384
	global_load_dword v94, v[72:73], off offset:448
	s_waitcnt vmcnt(7)
	v_pk_mul_f32 v[34:35], v[34:35], v[80:81] op_sel_hi:[1,0]
	v_pk_mul_f32 v[36:37], v[36:37], v[80:81] op_sel_hi:[1,0]
	s_waitcnt vmcnt(6)
	v_pk_mul_f32 v[38:39], v[38:39], v[82:83] op_sel_hi:[1,0]
	v_pk_mul_f32 v[40:41], v[40:41], v[82:83] op_sel_hi:[1,0]
	s_waitcnt vmcnt(5)
	v_pk_mul_f32 v[42:43], v[42:43], v[84:85] op_sel_hi:[1,0]
	v_pk_mul_f32 v[44:45], v[44:45], v[84:85] op_sel_hi:[1,0]
	s_waitcnt vmcnt(4)
	v_pk_mul_f32 v[46:47], v[46:47], v[86:87] op_sel_hi:[1,0]
	v_pk_mul_f32 v[48:49], v[48:49], v[86:87] op_sel_hi:[1,0]
	s_waitcnt vmcnt(3)
	v_pk_mul_f32 v[54:55], v[54:55], v[88:89] op_sel_hi:[1,0]
	v_pk_mul_f32 v[56:57], v[56:57], v[88:89] op_sel_hi:[1,0]
	s_waitcnt vmcnt(2)
	v_pk_mul_f32 v[50:51], v[50:51], v[90:91] op_sel_hi:[1,0]
	v_pk_mul_f32 v[52:53], v[52:53], v[90:91] op_sel_hi:[1,0]
	s_waitcnt vmcnt(1)
	v_pk_mul_f32 v[62:63], v[62:63], v[92:93] op_sel_hi:[1,0]
	v_pk_mul_f32 v[64:65], v[64:65], v[92:93] op_sel_hi:[1,0]
	s_waitcnt vmcnt(0)
	v_pk_mul_f32 v[58:59], v[58:59], v[94:95] op_sel_hi:[1,0]
	v_pk_mul_f32 v[60:61], v[60:61], v[94:95] op_sel_hi:[1,0]
	s_branch .LBB0_47

; __device__ __forceinline__ unsigned pk2(float lo, float hi) { hwf2 v = {lo, hi}; return __builtin_bit_cast(unsigned, __builtin_convertvector(v, hwbf2)); }
; __device__ __forceinline__ void phase_cast_ss(const float* __restrict__ x, bf16_t* __restrict__ ob, float* __restrict__ ssq) {
;     ...
;   for (int row = gw; row < T_TOK; row += nw) {
;     const float4* xr = (const float4*)(x + (size_t)row * DM);
;     float4 v[16];
; #pragma unroll
;     for (int i = 0; i < 16; ++i) v[i] = xr[lane + 64 * i];
;     float ss = 0.f;
; #pragma unroll
;     for (int i = 0; i < 16; ++i) {
;       ss += v[i].x * v[i].x + v[i].y * v[i].y + v[i].z * v[i].z + v[i].w * v[i].w;
;       uint2 o; o.x = pk2(v[i].x, v[i].y); o.y = pk2(v[i].z, v[i].w);
;       *(uint2*)(ob + pk_off(row, (lane + 64 * i) * 4)) = o;
;     }
.LBB0_58:
	global_load_dwordx4 v[36:39], v[18:19], off nt
	global_load_dwordx4 v[40:43], v[18:19], off offset:1024 nt
	global_load_dwordx4 v[44:47], v[18:19], off offset:2048 nt
	global_load_dwordx4 v[48:51], v[18:19], off offset:3072 nt
	v_add_co_u32_e32 v2, vcc, s18, v18
	v_lshrrev_b32_e32 v22, 4, v34
	s_waitcnt lgkmcnt(0)
	v_addc_co_u32_e32 v3, vcc, 0, v19, vcc
	v_add_co_u32_e32 v10, vcc, s19, v18
	v_ashrrev_i32_e32 v23, 1, v14
	s_nop 0
	v_addc_co_u32_e32 v11, vcc, 0, v19, vcc
	global_load_dwordx4 v[52:55], v[2:3], off offset:1024 nt
	global_load_dwordx4 v[56:59], v[10:11], off offset:-4096 nt
	global_load_dwordx4 v[60:63], v[2:3], off offset:2048 nt
	global_load_dwordx4 v[64:67], v[2:3], off offset:3072 nt
	v_add_co_u32_e32 v12, vcc, s20, v18
	v_and_b32_e32 v24, 32, v22
	s_nop 0
	v_addc_co_u32_e32 v13, vcc, 0, v19, vcc
	global_load_dwordx4 v[6:9], v[12:13], off offset:1024 nt
	global_load_dwordx4 v[2:5], v[12:13], off offset:2048 nt
	global_load_dwordx4 v[68:71], v[10:11], off nt
	global_load_dwordx4 v[72:75], v[12:13], off nt
	global_load_dwordx4 v[76:79], v[10:11], off offset:1024 nt
	global_load_dwordx4 v[80:83], v[10:11], off offset:2048 nt
	global_load_dwordx4 v[84:87], v[10:11], off offset:3072 nt
	v_and_or_b32 v22, v23, s22, v27
	global_load_dwordx4 v[10:13], v[12:13], off offset:3072 nt
	v_lshrrev_b32_e32 v15, 3, v14
	v_ashrrev_i32_e32 v23, 31, v22
	v_and_or_b32 v15, v15, 14, v1
	v_lshlrev_b64 v[96:97], 14, v[22:23]
	v_and_or_b32 v20, v34, s21, v26
	v_lshlrev_b32_e32 v15, 10, v15
	v_or_b32_e32 v88, 4, v22
	v_or_b32_e32 v90, 8, v22
	v_or_b32_e32 v92, 12, v22
	v_or_b32_e32 v94, 16, v22
	v_bitop3_b32 v20, v15, v20, v24 bitop3:0xf6
	v_ashrrev_i32_e32 v89, 31, v88
	v_ashrrev_i32_e32 v91, 31, v90
	v_ashrrev_i32_e32 v93, 31, v92
	v_ashrrev_i32_e32 v95, 31, v94
	v_lshl_add_u64 v[24:25], s[8:9], 0, v[20:21]
	v_lshlrev_b64 v[88:89], 14, v[88:89]
	v_lshlrev_b64 v[90:91], 14, v[90:91]
	v_lshlrev_b64 v[92:93], 14, v[92:93]
	v_lshlrev_b64 v[94:95], 14, v[94:95]
	v_lshl_add_u64 v[96:97], v[24:25], 0, v[96:97]
	v_lshl_add_u64 v[88:89], v[24:25], 0, v[88:89]
	v_lshl_add_u64 v[90:91], v[24:25], 0, v[90:91]
	v_lshl_add_u64 v[92:93], v[24:25], 0, v[92:93]
	v_lshl_add_u64 v[94:95], v[24:25], 0, v[94:95]
	s_waitcnt vmcnt(15)
	v_pk_mul_f32 v[98:99], v[36:37], v[36:37]
	s_waitcnt vmcnt(14)
	v_pk_mul_f32 v[100:101], v[40:41], v[40:41]
	v_cvt_pk_bf16_f32 v36, v36, v37
	v_cvt_pk_bf16_f32 v37, v38, v39
	v_pk_mul_f32 v[38:39], v[38:39], v[38:39]
	v_cvt_pk_bf16_f32 v40, v40, v41
	v_cvt_pk_bf16_f32 v41, v42, v43
	v_pk_mul_f32 v[42:43], v[42:43], v[42:43]
	v_add_f32_e32 v23, v100, v101
	v_add_f32_e32 v35, v98, v99
	v_add_f32_e32 v23, v23, v42
	v_add_f32_e32 v35, v35, v38
	s_waitcnt vmcnt(13)
	v_pk_mul_f32 v[102:103], v[44:45], v[44:45]
	v_add_f32_e32 v23, v23, v43
	v_add_f32_e32 v35, v35, v39
	v_cvt_pk_bf16_f32 v44, v44, v45
	v_cvt_pk_bf16_f32 v45, v46, v47
	v_pk_mul_f32 v[46:47], v[46:47], v[46:47]
	v_add_f32_e32 v23, v35, v23
	v_add_f32_e32 v35, v102, v103
	v_add_f32_e32 v35, v35, v46
	s_waitcnt vmcnt(12)
	v_pk_mul_f32 v[104:105], v[48:49], v[48:49]
	v_cvt_pk_bf16_f32 v48, v48, v49
	v_cvt_pk_bf16_f32 v49, v50, v51
	global_store_dwordx2 v[96:97], v[36:37], off
	global_store_dwordx2 v[88:89], v[40:41], off
	global_store_dwordx2 v[90:91], v[44:45], off
	global_store_dwordx2 v[92:93], v[48:49], off
	s_waitcnt vmcnt(14)
	v_cvt_pk_bf16_f32 v44, v56, v57
	v_cvt_pk_bf16_f32 v45, v58, v59
	v_add_f32_e32 v35, v35, v47
	v_pk_mul_f32 v[50:51], v[50:51], v[50:51]
	v_pk_mul_f32 v[36:37], v[52:53], v[52:53]
	v_pk_mul_f32 v[40:41], v[56:57], v[56:57]
	global_store_dwordx2 v[94:95], v[44:45], off
	v_pk_mul_f32 v[44:45], v[54:55], v[54:55]
	v_cvt_pk_bf16_f32 v52, v52, v53
	v_cvt_pk_bf16_f32 v53, v54, v55
	v_or_b32_e32 v54, 20, v22
	v_add_f32_e32 v23, v23, v35
	v_add_f32_e32 v35, v104, v105
	v_pk_mul_f32 v[48:49], v[58:59], v[58:59]
	v_ashrrev_i32_e32 v55, 31, v54
	v_add_f32_e32 v20, v40, v41
	v_add_f32_e32 v35, v35, v50
	v_lshlrev_b64 v[54:55], 14, v[54:55]
	v_add_f32_e32 v15, v36, v37
	v_add_f32_e32 v20, v20, v48
	v_add_f32_e32 v35, v35, v51
	v_lshl_add_u64 v[54:55], v[24:25], 0, v[54:55]
	v_or_b32_e32 v58, 24, v22
	v_add_f32_e32 v15, v15, v44
	v_add_f32_e32 v20, v20, v49
	v_add_f32_e32 v23, v23, v35
	global_store_dwordx2 v[54:55], v[52:53], off
	s_waitcnt vmcnt(15)
	v_pk_mul_f32 v[52:53], v[60:61], v[60:61]
	v_ashrrev_i32_e32 v59, 31, v58
	v_add_f32_e32 v15, v15, v45
	v_add_f32_e32 v20, v23, v20
	v_pk_mul_f32 v[54:55], v[62:63], v[62:63]
	v_lshlrev_b64 v[58:59], 14, v[58:59]
	v_add_f32_e32 v15, v20, v15
	v_add_f32_e32 v20, v52, v53
	v_cvt_pk_bf16_f32 v56, v60, v61
	v_cvt_pk_bf16_f32 v57, v62, v63
	v_lshl_add_u64 v[58:59], v[24:25], 0, v[58:59]
	v_or_b32_e32 v62, 28, v22
	v_add_f32_e32 v20, v20, v54
	global_store_dwordx2 v[58:59], v[56:57], off
	s_waitcnt vmcnt(15)
; __device__ __forceinline__ unsigned pk2(float lo, float hi) { hwf2 v = {lo, hi}; return __builtin_bit_cast(unsigned, __builtin_convertvector(v, hwbf2)); }
; __device__ __forceinline__ float shfl_lane(float x, int src_lane) { return __int_as_float(__builtin_amdgcn_ds_bpermute(src_lane << 2, __float_as_int(x))); }
; __device__ __forceinline__ void phase_cast_ss(const float* __restrict__ x, bf16_t* __restrict__ ob, float* __restrict__ ssq) {
;     ...
; #pragma unroll
;     for (int i = 0; i < 16; ++i) {
;       ss += v[i].x * v[i].x + v[i].y * v[i].y + v[i].z * v[i].z + v[i].w * v[i].w;
;       uint2 o; o.x = pk2(v[i].x, v[i].y); o.y = pk2(v[i].z, v[i].w);
;       *(uint2*)(ob + pk_off(row, (lane + 64 * i) * 4)) = o;
;     }
; #pragma unroll
;     for (int o = 32; o >= 1; o >>= 1) ss += shfl_lane(ss, lane ^ o);
;     if (lane == 0) ssq[row] = ss;
;   }
	v_pk_mul_f32 v[56:57], v[64:65], v[64:65]
	v_ashrrev_i32_e32 v63, 31, v62
	v_add_f32_e32 v20, v20, v55
	v_pk_mul_f32 v[58:59], v[66:67], v[66:67]
	v_lshlrev_b64 v[62:63], 14, v[62:63]
	v_add_f32_e32 v15, v15, v20
	v_add_f32_e32 v20, v56, v57
	v_cvt_pk_bf16_f32 v60, v64, v65
	v_cvt_pk_bf16_f32 v61, v66, v67
	v_lshl_add_u64 v[62:63], v[24:25], 0, v[62:63]
	v_or_b32_e32 v66, 32, v22
	v_add_f32_e32 v20, v20, v58
	global_store_dwordx2 v[62:63], v[60:61], off
	s_waitcnt vmcnt(13)
	v_pk_mul_f32 v[60:61], v[68:69], v[68:69]
	v_ashrrev_i32_e32 v67, 31, v66
	v_add_f32_e32 v20, v20, v59
	v_pk_mul_f32 v[62:63], v[70:71], v[70:71]
	v_lshlrev_b64 v[66:67], 14, v[66:67]
	v_add_f32_e32 v15, v15, v20
	v_add_f32_e32 v20, v60, v61
	v_cvt_pk_bf16_f32 v64, v68, v69
	v_cvt_pk_bf16_f32 v65, v70, v71
	v_lshl_add_u64 v[66:67], v[24:25], 0, v[66:67]
	v_or_b32_e32 v70, 36, v22
	v_add_f32_e32 v20, v20, v62
	global_store_dwordx2 v[66:67], v[64:65], off
	s_waitcnt vmcnt(12)
	v_pk_mul_f32 v[64:65], v[76:77], v[76:77]
	v_ashrrev_i32_e32 v71, 31, v70
	v_add_f32_e32 v20, v20, v63
	v_pk_mul_f32 v[66:67], v[78:79], v[78:79]
	v_lshlrev_b64 v[70:71], 14, v[70:71]
	v_add_f32_e32 v15, v15, v20
	v_add_f32_e32 v20, v64, v65
	v_cvt_pk_bf16_f32 v68, v76, v77
	v_cvt_pk_bf16_f32 v69, v78, v79
	v_lshl_add_u64 v[70:71], v[24:25], 0, v[70:71]
	v_or_b32_e32 v78, 40, v22
	v_add_f32_e32 v20, v20, v66
	global_store_dwordx2 v[70:71], v[68:69], off
	s_waitcnt vmcnt(12)
	v_pk_mul_f32 v[68:69], v[80:81], v[80:81]
	v_ashrrev_i32_e32 v79, 31, v78
	v_add_f32_e32 v20, v20, v67
	v_pk_mul_f32 v[70:71], v[82:83], v[82:83]
	v_lshlrev_b64 v[78:79], 14, v[78:79]
	v_add_f32_e32 v15, v15, v20
	v_add_f32_e32 v20, v68, v69
	v_cvt_pk_bf16_f32 v76, v80, v81
	v_cvt_pk_bf16_f32 v77, v82, v83
	v_lshl_add_u64 v[78:79], v[24:25], 0, v[78:79]
	v_or_b32_e32 v82, 44, v22
	v_add_f32_e32 v20, v20, v70
	global_store_dwordx2 v[78:79], v[76:77], off
	s_waitcnt vmcnt(12)
	v_pk_mul_f32 v[76:77], v[84:85], v[84:85]
	v_ashrrev_i32_e32 v83, 31, v82
	v_add_f32_e32 v20, v20, v71
	v_pk_mul_f32 v[78:79], v[86:87], v[86:87]
	v_lshlrev_b64 v[82:83], 14, v[82:83]
	v_add_f32_e32 v15, v15, v20
	v_add_f32_e32 v20, v76, v77
	v_cvt_pk_bf16_f32 v80, v84, v85
	v_cvt_pk_bf16_f32 v81, v86, v87
	v_lshl_add_u64 v[82:83], v[24:25], 0, v[82:83]
	v_add_f32_e32 v20, v20, v78
	global_store_dwordx2 v[82:83], v[80:81], off
	v_pk_mul_f32 v[80:81], v[72:73], v[72:73]
	v_add_f32_e32 v20, v20, v79
	v_pk_mul_f32 v[82:83], v[74:75], v[74:75]
	v_add_f32_e32 v15, v15, v20
	v_add_f32_e32 v20, v80, v81
	v_add_f32_e32 v20, v20, v82
	v_pk_mul_f32 v[84:85], v[6:7], v[6:7]
	v_add_f32_e32 v20, v20, v83
	v_pk_mul_f32 v[86:87], v[8:9], v[8:9]
	v_add_f32_e32 v15, v15, v20
	v_add_f32_e32 v20, v84, v85
	v_add_f32_e32 v20, v20, v86
	v_pk_mul_f32 v[36:37], v[2:3], v[2:3]
	v_add_f32_e32 v20, v20, v87
	v_pk_mul_f32 v[40:41], v[4:5], v[4:5]
	v_add_f32_e32 v15, v15, v20
	v_add_f32_e32 v20, v36, v37
	v_add_f32_e32 v20, v20, v40
	s_waitcnt vmcnt(12)
	v_pk_mul_f32 v[44:45], v[10:11], v[10:11]
	v_add_f32_e32 v20, v20, v41
	v_pk_mul_f32 v[42:43], v[12:13], v[12:13]
	v_add_f32_e32 v15, v15, v20
	v_add_f32_e32 v20, v44, v45
	v_add_f32_e32 v20, v20, v42
	v_add_f32_e32 v20, v20, v43
	v_add_f32_e32 v15, v15, v20
	ds_bpermute_b32 v20, v28, v15
	v_cvt_pk_bf16_f32 v6, v6, v7
	v_cvt_pk_bf16_f32 v7, v8, v9
	v_or_b32_e32 v8, 52, v22
	v_ashrrev_i32_e32 v9, 31, v8
	s_waitcnt lgkmcnt(0)
	v_add_f32_e32 v15, v15, v20
	ds_bpermute_b32 v20, v29, v15
	v_lshlrev_b64 v[8:9], 14, v[8:9]
	v_lshl_add_u64 v[8:9], v[24:25], 0, v[8:9]
	global_store_dwordx2 v[8:9], v[6:7], off
	v_cvt_pk_bf16_f32 v2, v2, v3
	s_waitcnt lgkmcnt(0)
	v_add_f32_e32 v15, v15, v20
	ds_bpermute_b32 v20, v30, v15
	v_cvt_pk_bf16_f32 v3, v4, v5
	v_or_b32_e32 v4, 56, v22
	v_ashrrev_i32_e32 v5, 31, v4
	v_lshlrev_b64 v[4:5], 14, v[4:5]
	s_waitcnt lgkmcnt(0)
	v_add_f32_e32 v6, v15, v20
	ds_bpermute_b32 v7, v31, v6
	v_lshl_add_u64 v[4:5], v[24:25], 0, v[4:5]
	global_store_dwordx2 v[4:5], v[2:3], off
	v_cvt_pk_bf16_f32 v72, v72, v73
	v_cvt_pk_bf16_f32 v73, v74, v75
	s_waitcnt lgkmcnt(0)
	v_add_f32_e32 v7, v6, v7
	ds_bpermute_b32 v8, v32, v7
	v_or_b32_e32 v74, 48, v22
	v_or_b32_e32 v6, 60, v22
	v_ashrrev_i32_e32 v75, 31, v74
	v_lshlrev_b64 v[36:37], 14, v[74:75]
	s_waitcnt lgkmcnt(0)
	v_add_f32_e32 v2, v7, v8
	ds_bpermute_b32 v3, v33, v2
	v_ashrrev_i32_e32 v7, 31, v6
	v_lshlrev_b64 v[6:7], 14, v[6:7]
	v_lshl_add_u64 v[36:37], v[24:25], 0, v[36:37]
	v_cvt_pk_bf16_f32 v4, v10, v11
	v_cvt_pk_bf16_f32 v5, v12, v13
	v_lshl_add_u64 v[6:7], v[24:25], 0, v[6:7]
	global_store_dwordx2 v[36:37], v[72:73], off
	global_store_dwordx2 v[6:7], v[4:5], off
	s_and_saveexec_b64 s[16:17], s[6:7]
	s_cbranch_execz .LBB0_57
	s_waitcnt lgkmcnt(0)
	v_add_f32_e32 v2, v2, v3
	global_store_dword v[16:17], v2, off
	s_branch .LBB0_57

; __device__ __forceinline__ F8 wload(const WTile& w) {
;   F8 v; const size_t st = (size_t)16 * w.N;
;   v.a = *(const float4*)(w.src);          v.b = *(const float4*)(w.src + st);     v.c = *(const float4*)(w.src + 2 * st); v.d = *(const float4*)(w.src + 3 * st);
;   v.e = *(const float4*)(w.src + 4 * st); v.f = *(const float4*)(w.src + 5 * st); v.g = *(const float4*)(w.src + 6 * st); v.h = *(const float4*)(w.src + 7 * st);
;   if (w.gain) {
;     ...
;     WSC(v.a, 0) WSC(v.b, 1) WSC(v.c, 2) WSC(v.d, 3) WSC(v.e, 4) WSC(v.f, 5) WSC(v.g, 6) WSC(v.h, 7)
;     ...
;   }
.LBB0_153:
	v_add_u32_e32 v0, s10, v0
	v_mad_i64_i32 v[2:3], s[14:15], s8, v0, 0
	s_lshl_b32 s9, s13, 2
	v_lshlrev_b32_e32 v0, 2, v36
	s_and_b32 s88, s9, 0x7fffff80
	v_and_b32_e32 v37, 0x7c, v0
	v_lshl_add_u64 v[2:3], v[2:3], 2, s[6:7]
	v_lshl_add_u64 v[2:3], s[88:89], 2, v[2:3]
	v_lshlrev_b32_e32 v0, 2, v37
	v_lshl_add_u64 v[2:3], v[2:3], 0, v[0:1]
	s_lshl_b32 s6, s8, 6
	s_mov_b32 s7, s89
	v_lshl_add_u64 v[10:11], v[2:3], 0, s[6:7]
	global_load_dwordx4 v[6:9], v[2:3], off nt
	s_nop 0
	global_load_dwordx4 v[2:5], v[10:11], off nt
	v_lshl_add_u64 v[10:11], v[10:11], 0, s[6:7]
	v_lshl_add_u64 v[18:19], v[10:11], 0, s[6:7]
	global_load_dwordx4 v[14:17], v[10:11], off nt
	s_waitcnt lgkmcnt(0)
	global_load_dwordx4 v[10:13], v[18:19], off nt
	v_lshl_add_u64 v[18:19], v[18:19], 0, s[6:7]
	v_lshl_add_u64 v[26:27], v[18:19], 0, s[6:7]
	global_load_dwordx4 v[18:21], v[18:19], off nt
	s_nop 0
	global_load_dwordx4 v[22:25], v[26:27], off nt
	v_lshl_add_u64 v[26:27], v[26:27], 0, s[6:7]
	v_lshl_add_u64 v[30:31], v[26:27], 0, s[6:7]
	global_load_dwordx4 v[26:29], v[26:27], off nt
	s_nop 0
	global_load_dwordx4 v[30:33], v[30:31], off nt
	v_cmp_ne_u64_e32 vcc, 0, v[34:35]
	s_and_saveexec_b64 s[6:7], vcc
	s_cbranch_execz .LBB0_155
	global_load_dword v38, v[34:35], off
	s_waitcnt vmcnt(0)
	v_pk_mul_f32 v[6:7], v[6:7], v[38:39] op_sel_hi:[1,0]
	v_pk_mul_f32 v[8:9], v[8:9], v[38:39] op_sel_hi:[1,0]
	global_load_dword v38, v[34:35], off offset:64
	s_waitcnt vmcnt(0)
	v_pk_mul_f32 v[2:3], v[2:3], v[38:39] op_sel_hi:[1,0]
	v_pk_mul_f32 v[4:5], v[4:5], v[38:39] op_sel_hi:[1,0]
	global_load_dword v38, v[34:35], off offset:128
	s_waitcnt vmcnt(0)
	v_pk_mul_f32 v[14:15], v[14:15], v[38:39] op_sel_hi:[1,0]
	v_pk_mul_f32 v[16:17], v[16:17], v[38:39] op_sel_hi:[1,0]
	global_load_dword v38, v[34:35], off offset:192
	s_waitcnt vmcnt(0)
	v_pk_mul_f32 v[10:11], v[10:11], v[38:39] op_sel_hi:[1,0]
	v_pk_mul_f32 v[12:13], v[12:13], v[38:39] op_sel_hi:[1,0]
	global_load_dword v38, v[34:35], off offset:256
	s_waitcnt vmcnt(0)
	v_pk_mul_f32 v[18:19], v[18:19], v[38:39] op_sel_hi:[1,0]
	v_pk_mul_f32 v[20:21], v[20:21], v[38:39] op_sel_hi:[1,0]
	global_load_dword v38, v[34:35], off offset:320
	s_waitcnt vmcnt(0)
	v_pk_mul_f32 v[22:23], v[22:23], v[38:39] op_sel_hi:[1,0]
	v_pk_mul_f32 v[24:25], v[24:25], v[38:39] op_sel_hi:[1,0]
	global_load_dword v38, v[34:35], off offset:384
	s_waitcnt vmcnt(0)
	v_pk_mul_f32 v[26:27], v[26:27], v[38:39] op_sel_hi:[1,0]
	global_load_dword v34, v[34:35], off offset:448
	v_pk_mul_f32 v[28:29], v[28:29], v[38:39] op_sel_hi:[1,0]
	s_waitcnt vmcnt(0)
	v_pk_mul_f32 v[30:31], v[30:31], v[34:35] op_sel_hi:[1,0]
	v_pk_mul_f32 v[32:33], v[32:33], v[34:35] op_sel_hi:[1,0]

; __device__ __forceinline__ F8 wload(const WTile& w) {
;   F8 v; const size_t st = (size_t)16 * w.N;
;   v.a = *(const float4*)(w.src);          v.b = *(const float4*)(w.src + st);     v.c = *(const float4*)(w.src + 2 * st); v.d = *(const float4*)(w.src + 3 * st);
;   v.e = *(const float4*)(w.src + 4 * st); v.f = *(const float4*)(w.src + 5 * st); v.g = *(const float4*)(w.src + 6 * st); v.h = *(const float4*)(w.src + 7 * st);
;   if (w.gain) {
;     ...
;     WSC(v.a, 0) WSC(v.b, 1) WSC(v.c, 2) WSC(v.d, 3) WSC(v.e, 4) WSC(v.f, 5) WSC(v.g, 6) WSC(v.h, 7)
;     ...
;   }
.LBB0_162:
	v_add_u32_e32 v34, s14, v66
	v_mad_i64_i32 v[34:35], s[4:5], s10, v34, 0
	s_lshl_b32 s4, s15, 7
	s_ashr_i32 s5, s4, 31
	v_lshl_add_u64 v[34:35], v[34:35], 2, s[8:9]
	v_lshl_add_u64 v[34:35], s[4:5], 2, v[34:35]
	v_lshl_add_u64 v[34:35], v[34:35], 0, v[0:1]
	s_lshl_b32 s88, s10, 6
	v_lshl_add_u64 v[42:43], v[34:35], 0, s[88:89]
	global_load_dwordx4 v[34:37], v[34:35], off nt
	s_nop 0
	global_load_dwordx4 v[38:41], v[42:43], off nt
	v_lshl_add_u64 v[42:43], v[42:43], 0, s[88:89]
	v_lshl_add_u64 v[50:51], v[42:43], 0, s[88:89]
	global_load_dwordx4 v[42:45], v[42:43], off nt
	s_nop 0
	global_load_dwordx4 v[46:49], v[50:51], off nt
	v_lshl_add_u64 v[50:51], v[50:51], 0, s[88:89]
	v_lshl_add_u64 v[58:59], v[50:51], 0, s[88:89]
	global_load_dwordx4 v[54:57], v[50:51], off nt
	s_nop 0
	global_load_dwordx4 v[50:53], v[58:59], off nt
	v_lshl_add_u64 v[58:59], v[58:59], 0, s[88:89]
	v_lshl_add_u64 v[60:61], v[58:59], 0, s[88:89]
	global_load_dwordx4 v[62:65], v[58:59], off nt
	s_nop 0
	global_load_dwordx4 v[58:61], v[60:61], off nt
	v_cmp_ne_u64_e32 vcc, 0, v[70:71]
	s_and_saveexec_b64 s[8:9], vcc
	s_cbranch_execz .LBB0_156
	global_load_dword v78, v[70:71], off
	s_waitcnt vmcnt(0)
	v_pk_mul_f32 v[34:35], v[34:35], v[78:79] op_sel_hi:[1,0]
	v_pk_mul_f32 v[36:37], v[36:37], v[78:79] op_sel_hi:[1,0]
	global_load_dword v78, v[70:71], off offset:64
	s_waitcnt vmcnt(0)
	v_pk_mul_f32 v[38:39], v[38:39], v[78:79] op_sel_hi:[1,0]
	v_pk_mul_f32 v[40:41], v[40:41], v[78:79] op_sel_hi:[1,0]
	global_load_dword v78, v[70:71], off offset:128
	s_waitcnt vmcnt(0)
	v_pk_mul_f32 v[42:43], v[42:43], v[78:79] op_sel_hi:[1,0]
	v_pk_mul_f32 v[44:45], v[44:45], v[78:79] op_sel_hi:[1,0]
	global_load_dword v78, v[70:71], off offset:192
	s_waitcnt vmcnt(0)
	v_pk_mul_f32 v[46:47], v[46:47], v[78:79] op_sel_hi:[1,0]
	v_pk_mul_f32 v[48:49], v[48:49], v[78:79] op_sel_hi:[1,0]
	global_load_dword v78, v[70:71], off offset:256
	s_waitcnt vmcnt(0)
	v_pk_mul_f32 v[54:55], v[54:55], v[78:79] op_sel_hi:[1,0]
	v_pk_mul_f32 v[56:57], v[56:57], v[78:79] op_sel_hi:[1,0]
	global_load_dword v78, v[70:71], off offset:320
	s_waitcnt vmcnt(0)
	v_pk_mul_f32 v[50:51], v[50:51], v[78:79] op_sel_hi:[1,0]
	v_pk_mul_f32 v[52:53], v[52:53], v[78:79] op_sel_hi:[1,0]
	global_load_dword v78, v[70:71], off offset:384
	s_waitcnt vmcnt(0)
	v_pk_mul_f32 v[62:63], v[62:63], v[78:79] op_sel_hi:[1,0]
	global_load_dword v70, v[70:71], off offset:448
	v_pk_mul_f32 v[64:65], v[64:65], v[78:79] op_sel_hi:[1,0]
	s_waitcnt vmcnt(0)
	v_pk_mul_f32 v[58:59], v[58:59], v[70:71] op_sel_hi:[1,0]
	v_pk_mul_f32 v[60:61], v[60:61], v[70:71] op_sel_hi:[1,0]
	s_branch .LBB0_156

; __device__ __forceinline__ F8 wload(const WTile& w) {
;   F8 v; const size_t st = (size_t)16 * w.N;
;   v.a = *(const float4*)(w.src);          v.b = *(const float4*)(w.src + st);     v.c = *(const float4*)(w.src + 2 * st); v.d = *(const float4*)(w.src + 3 * st);
;   v.e = *(const float4*)(w.src + 4 * st); v.f = *(const float4*)(w.src + 5 * st); v.g = *(const float4*)(w.src + 6 * st); v.h = *(const float4*)(w.src + 7 * st);
;   if (w.gain) {
;     ...
;     WSC(v.a, 0) WSC(v.b, 1) WSC(v.c, 2) WSC(v.d, 3) WSC(v.e, 4) WSC(v.f, 5) WSC(v.g, 6) WSC(v.h, 7)
;     ...
;   }
.LBB0_173:
	v_add_u32_e32 v0, s12, v0
	v_mad_i64_i32 v[2:3], s[6:7], s10, v0, 0
	s_lshl_b32 s6, s13, 7
	v_lshlrev_b32_e32 v0, 2, v36
	s_ashr_i32 s7, s6, 31
	v_and_b32_e32 v37, 0x7c, v0
	v_lshl_add_u64 v[2:3], v[2:3], 2, s[8:9]
	v_lshl_add_u64 v[2:3], s[6:7], 2, v[2:3]
	v_lshlrev_b32_e32 v0, 2, v37
	v_lshl_add_u64 v[2:3], v[2:3], 0, v[0:1]
	s_lshl_b32 s88, s10, 6
	v_lshl_add_u64 v[10:11], v[2:3], 0, s[88:89]
	global_load_dwordx4 v[6:9], v[2:3], off nt
	s_nop 0
	global_load_dwordx4 v[2:5], v[10:11], off nt
	v_lshl_add_u64 v[10:11], v[10:11], 0, s[88:89]
	v_lshl_add_u64 v[18:19], v[10:11], 0, s[88:89]
	global_load_dwordx4 v[14:17], v[10:11], off nt
	s_waitcnt lgkmcnt(0)
	global_load_dwordx4 v[10:13], v[18:19], off nt
	v_lshl_add_u64 v[18:19], v[18:19], 0, s[88:89]
	v_lshl_add_u64 v[26:27], v[18:19], 0, s[88:89]
	global_load_dwordx4 v[18:21], v[18:19], off nt
	s_nop 0
	global_load_dwordx4 v[22:25], v[26:27], off nt
	v_lshl_add_u64 v[26:27], v[26:27], 0, s[88:89]
	v_lshl_add_u64 v[30:31], v[26:27], 0, s[88:89]
	global_load_dwordx4 v[26:29], v[26:27], off nt
	s_nop 0
	global_load_dwordx4 v[30:33], v[30:31], off nt
	v_cmp_ne_u64_e32 vcc, 0, v[34:35]
	s_and_saveexec_b64 s[8:9], vcc
	s_cbranch_execz .LBB0_175
	global_load_dword v38, v[34:35], off
	s_waitcnt vmcnt(0)
	v_pk_mul_f32 v[6:7], v[6:7], v[38:39] op_sel_hi:[1,0]
	v_pk_mul_f32 v[8:9], v[8:9], v[38:39] op_sel_hi:[1,0]
	global_load_dword v38, v[34:35], off offset:64
	s_waitcnt vmcnt(0)
	v_pk_mul_f32 v[2:3], v[2:3], v[38:39] op_sel_hi:[1,0]
	v_pk_mul_f32 v[4:5], v[4:5], v[38:39] op_sel_hi:[1,0]
	global_load_dword v38, v[34:35], off offset:128
	s_waitcnt vmcnt(0)
	v_pk_mul_f32 v[14:15], v[14:15], v[38:39] op_sel_hi:[1,0]
	v_pk_mul_f32 v[16:17], v[16:17], v[38:39] op_sel_hi:[1,0]
	global_load_dword v38, v[34:35], off offset:192
	s_waitcnt vmcnt(0)
	v_pk_mul_f32 v[10:11], v[10:11], v[38:39] op_sel_hi:[1,0]
	v_pk_mul_f32 v[12:13], v[12:13], v[38:39] op_sel_hi:[1,0]
	global_load_dword v38, v[34:35], off offset:256
	s_waitcnt vmcnt(0)
	v_pk_mul_f32 v[18:19], v[18:19], v[38:39] op_sel_hi:[1,0]
	v_pk_mul_f32 v[20:21], v[20:21], v[38:39] op_sel_hi:[1,0]
	global_load_dword v38, v[34:35], off offset:320
	s_waitcnt vmcnt(0)
	v_pk_mul_f32 v[22:23], v[22:23], v[38:39] op_sel_hi:[1,0]
	v_pk_mul_f32 v[24:25], v[24:25], v[38:39] op_sel_hi:[1,0]
	global_load_dword v38, v[34:35], off offset:384
	s_waitcnt vmcnt(0)
	v_pk_mul_f32 v[26:27], v[26:27], v[38:39] op_sel_hi:[1,0]
	global_load_dword v34, v[34:35], off offset:448
	v_pk_mul_f32 v[28:29], v[28:29], v[38:39] op_sel_hi:[1,0]
	s_waitcnt vmcnt(0)
	v_pk_mul_f32 v[30:31], v[30:31], v[34:35] op_sel_hi:[1,0]
	v_pk_mul_f32 v[32:33], v[32:33], v[34:35] op_sel_hi:[1,0]

; __device__ __forceinline__ F8 wload(const WTile& w) {
;   F8 v; const size_t st = (size_t)16 * w.N;
;   v.a = *(const float4*)(w.src);          v.b = *(const float4*)(w.src + st);     v.c = *(const float4*)(w.src + 2 * st); v.d = *(const float4*)(w.src + 3 * st);
;   v.e = *(const float4*)(w.src + 4 * st); v.f = *(const float4*)(w.src + 5 * st); v.g = *(const float4*)(w.src + 6 * st); v.h = *(const float4*)(w.src + 7 * st);
;   if (w.gain) {
;     ...
;     WSC(v.a, 0) WSC(v.b, 1) WSC(v.c, 2) WSC(v.d, 3) WSC(v.e, 4) WSC(v.f, 5) WSC(v.g, 6) WSC(v.h, 7)
;     ...
;   }
.LBB0_182:
	v_add_u32_e32 v34, s15, v66
	v_mad_i64_i32 v[34:35], s[4:5], s12, v34, 0
	s_lshl_b32 s4, s16, 7
	s_ashr_i32 s5, s4, 31
	v_lshl_add_u64 v[34:35], v[34:35], 2, s[10:11]
	v_lshl_add_u64 v[34:35], s[4:5], 2, v[34:35]
	v_lshl_add_u64 v[34:35], v[34:35], 0, v[0:1]
	s_lshl_b32 s88, s12, 6
	v_lshl_add_u64 v[42:43], v[34:35], 0, s[88:89]
	global_load_dwordx4 v[34:37], v[34:35], off nt
	s_nop 0
	global_load_dwordx4 v[38:41], v[42:43], off nt
	v_lshl_add_u64 v[42:43], v[42:43], 0, s[88:89]
	v_lshl_add_u64 v[50:51], v[42:43], 0, s[88:89]
	global_load_dwordx4 v[42:45], v[42:43], off nt
	s_nop 0
	global_load_dwordx4 v[46:49], v[50:51], off nt
	v_lshl_add_u64 v[50:51], v[50:51], 0, s[88:89]
	v_lshl_add_u64 v[58:59], v[50:51], 0, s[88:89]
	global_load_dwordx4 v[54:57], v[50:51], off nt
	s_nop 0
	global_load_dwordx4 v[50:53], v[58:59], off nt
	v_lshl_add_u64 v[58:59], v[58:59], 0, s[88:89]
	v_lshl_add_u64 v[60:61], v[58:59], 0, s[88:89]
	global_load_dwordx4 v[62:65], v[58:59], off nt
	s_nop 0
	global_load_dwordx4 v[58:61], v[60:61], off nt
	v_cmp_ne_u64_e32 vcc, 0, v[70:71]
	s_and_saveexec_b64 s[10:11], vcc
	s_cbranch_execz .LBB0_176
	global_load_dword v78, v[70:71], off
	s_waitcnt vmcnt(0)
	v_pk_mul_f32 v[34:35], v[34:35], v[78:79] op_sel_hi:[1,0]
	v_pk_mul_f32 v[36:37], v[36:37], v[78:79] op_sel_hi:[1,0]
	global_load_dword v78, v[70:71], off offset:64
	s_waitcnt vmcnt(0)
	v_pk_mul_f32 v[38:39], v[38:39], v[78:79] op_sel_hi:[1,0]
	v_pk_mul_f32 v[40:41], v[40:41], v[78:79] op_sel_hi:[1,0]
	global_load_dword v78, v[70:71], off offset:128
	s_waitcnt vmcnt(0)
	v_pk_mul_f32 v[42:43], v[42:43], v[78:79] op_sel_hi:[1,0]
	v_pk_mul_f32 v[44:45], v[44:45], v[78:79] op_sel_hi:[1,0]
	global_load_dword v78, v[70:71], off offset:192
	s_waitcnt vmcnt(0)
	v_pk_mul_f32 v[46:47], v[46:47], v[78:79] op_sel_hi:[1,0]
	v_pk_mul_f32 v[48:49], v[48:49], v[78:79] op_sel_hi:[1,0]
	global_load_dword v78, v[70:71], off offset:256
	s_waitcnt vmcnt(0)
	v_pk_mul_f32 v[54:55], v[54:55], v[78:79] op_sel_hi:[1,0]
	v_pk_mul_f32 v[56:57], v[56:57], v[78:79] op_sel_hi:[1,0]
	global_load_dword v78, v[70:71], off offset:320
	s_waitcnt vmcnt(0)
	v_pk_mul_f32 v[50:51], v[50:51], v[78:79] op_sel_hi:[1,0]
	v_pk_mul_f32 v[52:53], v[52:53], v[78:79] op_sel_hi:[1,0]
	global_load_dword v78, v[70:71], off offset:384
	s_waitcnt vmcnt(0)
	v_pk_mul_f32 v[62:63], v[62:63], v[78:79] op_sel_hi:[1,0]
	global_load_dword v70, v[70:71], off offset:448
	v_pk_mul_f32 v[64:65], v[64:65], v[78:79] op_sel_hi:[1,0]
	s_waitcnt vmcnt(0)
	v_pk_mul_f32 v[58:59], v[58:59], v[70:71] op_sel_hi:[1,0]
	v_pk_mul_f32 v[60:61], v[60:61], v[70:71] op_sel_hi:[1,0]
	s_branch .LBB0_176
